# sample_branch: flat loads and store converted to global so the lgkmcnt(0) before the LDS-reduction barriers no longer drains the next-branch fragment prefetch; s_sleep removed from grid-barrier poll
# baseline (speedup 1.0000x reference)
.LBB0_161:
	s_and_b32 s4, s0, 0xffffffe0
	s_addk_i32 s4, 0x4000
	v_or_b32_e32 v0, s4, v144
	s_and_b32 s6, s1, 0x3c0
	v_add_u32_e32 v134, s4, v145
	v_mad_i64_i32 v[138:139], s[4:5], v0, s66, v[130:131]
	v_or_b32_e32 v0, s6, v144
	s_mov_b32 s4, 0x6a000
	v_lshlrev_b32_e32 v0, 11, v0
	v_add_co_u32_e32 v78, vcc, s4, v138
	v_lshl_add_u64 v[140:141], v[132:133], 0, v[0:1]
	s_nop 0
	v_addc_co_u32_e32 v79, vcc, 0, v139, vcc
	global_load_dwordx4 v[2:5], v[138:139], off
	v_add_co_u32_e32 v86, vcc, s14, v140
	global_load_dwordx4 v[6:9], v[78:79], off
	global_load_dwordx4 v[10:13], v[140:141], off
	v_addc_co_u32_e32 v87, vcc, 0, v141, vcc
	v_add_co_u32_e32 v90, vcc, s15, v140
	global_load_dwordx4 v[14:17], v[86:87], off
	s_nop 0
	v_addc_co_u32_e32 v91, vcc, 0, v141, vcc
	global_load_dwordx4 v[18:21], v[90:91], off
	v_add_co_u32_e32 v94, vcc, s16, v140
	v_or_b32_e32 v100, s6, v146
	s_nop 0
	v_addc_co_u32_e32 v95, vcc, 0, v141, vcc
	global_load_dwordx4 v[22:25], v[94:95], off
	global_load_dwordx4 v[26:29], v[138:139], off offset:64
	global_load_dwordx4 v[30:33], v[78:79], off offset:64
	global_load_dwordx4 v[34:37], v[140:141], off offset:64
	global_load_dwordx4 v[38:41], v[86:87], off offset:64
	global_load_dwordx4 v[42:45], v[90:91], off offset:64
	global_load_dwordx4 v[46:49], v[94:95], off offset:64
	global_load_dwordx4 v[50:53], v[138:139], off offset:128
	global_load_dwordx4 v[54:57], v[78:79], off offset:128
	global_load_dwordx4 v[58:61], v[140:141], off offset:128
	global_load_dwordx4 v[62:65], v[86:87], off offset:128
	global_load_dwordx4 v[66:69], v[90:91], off offset:128
	global_load_dwordx4 v[70:73], v[94:95], off offset:128
	global_load_dwordx4 v[74:77], v[138:139], off offset:192
	s_nop 0
	global_load_dwordx4 v[78:81], v[78:79], off offset:192
	s_nop 0
	global_load_dwordx4 v[82:85], v[140:141], off offset:192
	s_nop 0
	global_load_dwordx4 v[86:89], v[86:87], off offset:192
	s_nop 0
	global_load_dwordx4 v[90:93], v[90:91], off offset:192
	s_nop 0
	global_load_dwordx4 v[94:97], v[94:95], off offset:192
	v_mov_b64_e32 v[98:99], s[88:89]
	v_mad_i64_i32 v[98:99], s[4:5], v134, s66, v[98:99]
	v_lshlrev_b32_e32 v0, 1, v100
	v_lshl_add_u64 v[136:137], v[98:99], 0, v[0:1]
	s_mov_b32 s4, 0x218000
	v_lshl_add_u64 v[142:143], v[136:137], 0, s[18:19]
	v_ashrrev_i32_e32 v135, 31, v134
	s_add_i32 s2, s2, s3
	s_add_i32 s1, s1, s86
	s_add_i32 s0, s0, s87
	s_cmpk_gt_i32 s2, 0xff
	s_waitcnt vmcnt(0) lgkmcnt(0)
	v_mfma_f32_16x16x32_bf16 v[98:101], v[2:5], v[10:13], 0
	v_mfma_f32_16x16x32_bf16 v[102:105], v[2:5], v[14:17], 0
	v_mfma_f32_16x16x32_bf16 v[106:109], v[2:5], v[18:21], 0
	v_mfma_f32_16x16x32_bf16 v[2:5], v[2:5], v[22:25], 0
	v_mfma_f32_16x16x32_bf16 v[10:13], v[6:9], v[10:13], 0
	v_mfma_f32_16x16x32_bf16 v[14:17], v[6:9], v[14:17], 0
	v_mfma_f32_16x16x32_bf16 v[18:21], v[6:9], v[18:21], 0
	v_mfma_f32_16x16x32_bf16 v[6:9], v[6:9], v[22:25], 0
	v_mfma_f32_16x16x32_bf16 v[22:25], v[26:29], v[34:37], v[98:101]
	v_mfma_f32_16x16x32_bf16 v[98:101], v[26:29], v[38:41], v[102:105]
	v_mfma_f32_16x16x32_bf16 v[102:105], v[26:29], v[42:45], v[106:109]
	v_mfma_f32_16x16x32_bf16 v[2:5], v[26:29], v[46:49], v[2:5]
	v_mfma_f32_16x16x32_bf16 v[10:13], v[30:33], v[34:37], v[10:13]
	v_mfma_f32_16x16x32_bf16 v[14:17], v[30:33], v[38:41], v[14:17]
	v_mfma_f32_16x16x32_bf16 v[18:21], v[30:33], v[42:45], v[18:21]
	v_mfma_f32_16x16x32_bf16 v[6:9], v[30:33], v[46:49], v[6:9]
	v_mfma_f32_16x16x32_bf16 v[22:25], v[50:53], v[58:61], v[22:25]
	v_mfma_f32_16x16x32_bf16 v[26:29], v[50:53], v[62:65], v[98:101]
	v_mfma_f32_16x16x32_bf16 v[30:33], v[50:53], v[66:69], v[102:105]
	v_mfma_f32_16x16x32_bf16 v[2:5], v[50:53], v[70:73], v[2:5]
	v_mfma_f32_16x16x32_bf16 v[10:13], v[54:57], v[58:61], v[10:13]
	v_mfma_f32_16x16x32_bf16 v[14:17], v[54:57], v[62:65], v[14:17]
	v_mfma_f32_16x16x32_bf16 v[18:21], v[54:57], v[66:69], v[18:21]
	v_mfma_f32_16x16x32_bf16 v[6:9], v[54:57], v[70:73], v[6:9]
	v_mfma_f32_16x16x32_bf16 v[122:125], v[74:77], v[82:85], v[22:25]
	v_mfma_f32_16x16x32_bf16 v[126:129], v[74:77], v[86:89], v[26:29]
	v_mfma_f32_16x16x32_bf16 v[114:117], v[74:77], v[90:93], v[30:33]
	v_mfma_f32_16x16x32_bf16 v[118:121], v[74:77], v[94:97], v[2:5]
	v_add_co_u32_e32 v74, vcc, s4, v140
	s_mov_b32 s4, 0x210000
	s_nop 0
	v_addc_co_u32_e32 v75, vcc, 0, v141, vcc
	v_mfma_f32_16x16x32_bf16 v[106:109], v[78:81], v[82:85], v[10:13]
	global_load_dwordx4 v[2:5], v[74:75], off offset:192
	v_mfma_f32_16x16x32_bf16 v[110:113], v[78:81], v[86:89], v[14:17]
	v_mfma_f32_16x16x32_bf16 v[98:101], v[78:81], v[90:93], v[18:21]
	v_mfma_f32_16x16x32_bf16 v[102:105], v[78:81], v[94:97], v[6:9]
	v_add_co_u32_e32 v78, vcc, s4, v140
	s_mov_b32 s4, 0x208000
	s_nop 0
	v_addc_co_u32_e32 v79, vcc, 0, v141, vcc
	v_add_co_u32_e32 v82, vcc, s4, v140
	s_mov_b32 s4, 0x200000
	s_nop 0
	v_addc_co_u32_e32 v83, vcc, 0, v141, vcc
	v_add_co_u32_e32 v86, vcc, s4, v140
	s_mov_b32 s4, 0x6b000
	s_nop 0
	v_addc_co_u32_e32 v87, vcc, 0, v141, vcc
	v_add_co_u32_e32 v88, vcc, s4, v138
	global_load_dwordx4 v[6:9], v[78:79], off offset:192
	s_nop 0
	v_addc_co_u32_e32 v89, vcc, 0, v139, vcc
	v_add_co_u32_e32 v94, vcc, s12, v138
	global_load_dwordx4 v[10:13], v[82:83], off offset:192
	global_load_dwordx4 v[14:17], v[86:87], off offset:192
	v_addc_co_u32_e32 v95, vcc, 0, v139, vcc
	v_add_co_u32_e32 v150, vcc, s7, v136
	global_load_dwordx4 v[18:21], v[88:89], off offset:1248
	s_nop 0
	v_addc_co_u32_e32 v151, vcc, 0, v137, vcc
	global_load_dwordx4 v[22:25], v[94:95], off offset:1248
	global_load_dwordx4 v[26:29], v[74:75], off offset:128
	global_load_dwordx4 v[30:33], v[78:79], off offset:128
	global_load_dwordx4 v[34:37], v[82:83], off offset:128
	global_load_dwordx4 v[42:45], v[86:87], off offset:128
	global_load_dwordx4 v[38:41], v[88:89], off offset:1184
	global_load_dwordx4 v[46:49], v[94:95], off offset:1184
	global_load_dwordx4 v[50:53], v[74:75], off offset:64
	global_load_dwordx4 v[54:57], v[78:79], off offset:64
	global_load_dwordx4 v[58:61], v[82:83], off offset:64
	global_load_dwordx4 v[66:69], v[86:87], off offset:64
	global_load_dwordx4 v[62:65], v[88:89], off offset:1120
	global_load_dwordx4 v[70:73], v[94:95], off offset:1120
	s_nop 0
	global_load_dwordx4 v[74:77], v[74:75], off
	s_nop 0
	global_load_dwordx4 v[78:81], v[78:79], off
	s_nop 0
	global_load_dwordx4 v[82:85], v[82:83], off
	s_nop 0
	global_load_dwordx4 v[90:93], v[86:87], off
	s_nop 0
	global_load_dwordx4 v[86:89], v[88:89], off offset:1056
	s_nop 0
	global_load_dwordx4 v[94:97], v[94:95], off offset:1056
	s_mov_b32 s4, 0x418000
	global_load_dwordx2 v[150:151], v[150:151], off offset:2080
	s_waitcnt lgkmcnt(0)
	s_barrier
	ds_write2_b32 v148, v122, v126 offset1:16
	ds_write2_b32 v148, v123, v127 offset0:64 offset1:80
	ds_write2_b32 v148, v124, v128 offset0:128 offset1:144
	ds_write2_b32 v148, v125, v129 offset0:192 offset1:208
	ds_write2_b32 v148, v114, v118 offset0:32 offset1:48
	ds_write2_b32 v148, v115, v119 offset0:96 offset1:112
	ds_write2_b32 v148, v116, v120 offset0:160 offset1:176
	ds_write2_b32 v148, v117, v121 offset0:224 offset1:240
	v_add_u32_e32 v114, 0x1000, v148
	ds_write2_b32 v114, v106, v110 offset1:16
	ds_write2_b32 v114, v107, v111 offset0:64 offset1:80
	ds_write2_b32 v114, v108, v112 offset0:128 offset1:144
	ds_write2_b32 v114, v109, v113 offset0:192 offset1:208
	ds_write2_b32 v114, v98, v102 offset0:32 offset1:48
	ds_write2_b32 v114, v99, v103 offset0:96 offset1:112
	ds_write2_b32 v114, v100, v104 offset0:160 offset1:176
	ds_write2_b32 v114, v101, v105 offset0:224 offset1:240
	s_waitcnt lgkmcnt(0)
	s_barrier
	ds_read_b128 v[98:101], v147
	s_waitcnt vmcnt(0)
	v_mfma_f32_16x16x32_bf16 v[110:113], v[94:97], v[90:93], 0
	s_waitcnt lgkmcnt(0)
	v_pk_add_f32 v[102:103], v[100:101], 0 op_sel_hi:[1,0]
	v_pk_add_f32 v[104:105], v[98:99], 0 op_sel_hi:[1,0]
	ds_read_b128 v[98:101], v147 offset:8192
	v_mfma_f32_16x16x32_bf16 v[116:119], v[94:97], v[82:85], 0
	s_waitcnt lgkmcnt(0)
	v_pk_add_f32 v[102:103], v[102:103], v[100:101]
	v_pk_add_f32 v[104:105], v[104:105], v[98:99]
	ds_read_b128 v[98:101], v147 offset:16384
	v_mfma_f32_16x16x32_bf16 v[120:123], v[94:97], v[78:81], 0
	s_waitcnt lgkmcnt(0)
	v_pk_add_f32 v[102:103], v[102:103], v[100:101]
	v_pk_add_f32 v[104:105], v[104:105], v[98:99]
	ds_read_b128 v[98:101], v147 offset:24576
	v_mfma_f32_16x16x32_bf16 v[94:97], v[94:97], v[74:77], 0
	s_waitcnt lgkmcnt(0)
	v_pk_add_f32 v[102:103], v[102:103], v[100:101]
	v_pk_add_f32 v[104:105], v[104:105], v[98:99]
	ds_read_b128 v[98:101], v147 offset:32768
	v_mfma_f32_16x16x32_bf16 v[90:93], v[86:89], v[90:93], 0
	s_waitcnt lgkmcnt(0)
	v_pk_add_f32 v[102:103], v[102:103], v[100:101]
	v_pk_add_f32 v[104:105], v[104:105], v[98:99]
	ds_read_b128 v[98:101], v147 offset:40960
	v_mfma_f32_16x16x32_bf16 v[82:85], v[86:89], v[82:85], 0
	s_waitcnt lgkmcnt(0)
	v_pk_add_f32 v[102:103], v[102:103], v[100:101]
	v_pk_add_f32 v[104:105], v[104:105], v[98:99]
	ds_read_b128 v[98:101], v147 offset:49152
	v_mfma_f32_16x16x32_bf16 v[78:81], v[86:89], v[78:81], 0
	s_waitcnt lgkmcnt(0)
	v_pk_add_f32 v[106:107], v[102:103], v[100:101]
	ds_read_b128 v[100:103], v147 offset:57344
	v_pk_add_f32 v[104:105], v[104:105], v[98:99]
	v_mfma_f32_16x16x32_bf16 v[74:77], v[86:89], v[74:77], 0
	s_waitcnt lgkmcnt(0)
	v_pk_add_f32 v[98:99], v[106:107], v[102:103]
	v_lshlrev_b32_e32 v102, 16, v150
	v_mul_f32_e32 v102, 0xbfb8aa3b, v102
	v_exp_f32_e32 v102, v102
	v_mfma_f32_16x16x32_bf16 v[86:89], v[70:73], v[66:69], v[110:113]
	v_add_f32_e64 v100, v104, v100
	v_add_f32_e64 v101, v105, v101
	v_add_f32_e32 v102, 1.0, v102
	v_rcp_f32_e32 v108, v102
	v_and_b32_e32 v102, 0xffff0000, v150
	v_mul_f32_e32 v102, 0xbfb8aa3b, v102
	v_exp_f32_e32 v102, v102
	v_mfma_f32_16x16x32_bf16 v[110:113], v[70:73], v[58:61], v[116:119]
	v_add_f32_e32 v102, 1.0, v102
	v_mfma_f32_16x16x32_bf16 v[116:119], v[70:73], v[54:57], v[120:123]
	v_rcp_f32_e32 v106, v102
	v_lshlrev_b32_e32 v102, 16, v151
	v_mul_f32_e32 v102, 0xbfb8aa3b, v102
	v_add_co_u32_e32 v120, vcc, s4, v140
	s_mov_b32 s4, 0x410000
	s_nop 0
	v_addc_co_u32_e32 v121, vcc, 0, v141, vcc
	v_add_co_u32_e32 v124, vcc, s4, v140
	s_mov_b32 s4, 0x408000
	s_nop 0
	v_addc_co_u32_e32 v125, vcc, 0, v141, vcc
	v_mfma_f32_16x16x32_bf16 v[70:73], v[70:73], v[50:53], v[94:97]
	v_add_co_u32_e32 v128, vcc, s4, v140
	s_mov_b32 s4, 0x400000
	v_mfma_f32_16x16x32_bf16 v[66:69], v[62:65], v[66:69], v[90:93]
	v_addc_co_u32_e32 v129, vcc, 0, v141, vcc
	v_add_co_u32_e32 v154, vcc, s4, v140
	v_mfma_f32_16x16x32_bf16 v[58:61], v[62:65], v[58:61], v[82:85]
	v_exp_f32_e32 v102, v102
	v_addc_co_u32_e32 v155, vcc, 0, v141, vcc
	v_mfma_f32_16x16x32_bf16 v[54:57], v[62:65], v[54:57], v[78:81]
	s_mov_b32 s4, 0x6c000
	v_add_co_u32_e32 v158, vcc, s4, v138
	v_mfma_f32_16x16x32_bf16 v[50:53], v[62:65], v[50:53], v[74:77]
	s_nop 0
	v_addc_co_u32_e32 v159, vcc, 0, v139, vcc
	v_add_co_u32_e32 v162, vcc, s13, v138
	v_mfma_f32_16x16x32_bf16 v[62:65], v[46:49], v[42:45], v[86:89]
	v_add_f32_e32 v102, 1.0, v102
	v_addc_co_u32_e32 v163, vcc, 0, v139, vcc
	v_mfma_f32_16x16x32_bf16 v[74:77], v[46:49], v[34:37], v[110:113]
	v_rcp_f32_e32 v104, v102
	v_and_b32_e32 v102, 0xffff0000, v151
	v_mul_f32_e32 v102, 0xbfb8aa3b, v102
	v_mfma_f32_16x16x32_bf16 v[78:81], v[46:49], v[30:33], v[116:119]
	v_exp_f32_e32 v102, v102
	s_mov_b32 s4, 0x618000
	v_add_f32_e32 v102, 1.0, v102
	v_mfma_f32_16x16x32_bf16 v[46:49], v[46:49], v[26:29], v[70:73]
	v_rcp_f32_e32 v102, v102
	v_mfma_f32_16x16x32_bf16 v[42:45], v[38:41], v[42:45], v[66:69]
	v_mfma_f32_16x16x32_bf16 v[34:37], v[38:41], v[34:37], v[58:61]
	v_mfma_f32_16x16x32_bf16 v[30:33], v[38:41], v[30:33], v[54:57]
	v_mfma_f32_16x16x32_bf16 v[26:29], v[38:41], v[26:29], v[50:53]
	v_mfma_f32_16x16x32_bf16 v[38:41], v[22:25], v[14:17], v[62:65]
	v_mfma_f32_16x16x32_bf16 v[50:53], v[22:25], v[10:13], v[74:77]
	v_mfma_f32_16x16x32_bf16 v[54:57], v[22:25], v[6:9], v[78:81]
	v_mfma_f32_16x16x32_bf16 v[22:25], v[22:25], v[2:5], v[46:49]
	v_mfma_f32_16x16x32_bf16 v[14:17], v[18:21], v[14:17], v[42:45]
	v_mfma_f32_16x16x32_bf16 v[10:13], v[18:21], v[10:13], v[34:37]
	s_nop 1
	global_load_dwordx4 v[42:45], v[158:159], off offset:3296
	v_mfma_f32_16x16x32_bf16 v[6:9], v[18:21], v[6:9], v[30:33]
	global_load_dwordx4 v[34:37], v[154:155], off offset:192
	s_nop 1
	global_load_dwordx4 v[30:33], v[128:129], off offset:192
	v_mfma_f32_16x16x32_bf16 v[2:5], v[18:21], v[2:5], v[26:29]
	global_load_dwordx4 v[18:21], v[120:121], off offset:192
	s_nop 1
	global_load_dwordx4 v[26:29], v[124:125], off offset:192
	global_load_dwordx4 v[46:49], v[162:163], off offset:3296
	global_load_dwordx4 v[58:61], v[120:121], off offset:128
	global_load_dwordx4 v[62:65], v[124:125], off offset:128
	global_load_dwordx4 v[66:69], v[128:129], off offset:128
	global_load_dwordx4 v[70:73], v[154:155], off offset:128
	global_load_dwordx4 v[74:77], v[158:159], off offset:3232
	global_load_dwordx4 v[78:81], v[162:163], off offset:3232
	global_load_dwordx4 v[82:85], v[120:121], off offset:64
	global_load_dwordx4 v[86:89], v[124:125], off offset:64
	global_load_dwordx4 v[90:93], v[128:129], off offset:64
	global_load_dwordx4 v[94:97], v[154:155], off offset:64
	global_load_dwordx4 v[110:113], v[158:159], off offset:3168
	global_load_dwordx4 v[116:119], v[162:163], off offset:3168
	s_nop 0
	global_load_dwordx4 v[120:123], v[120:121], off
	s_nop 0
	global_load_dwordx4 v[124:127], v[124:125], off
	s_nop 0
	global_load_dwordx4 v[150:153], v[128:129], off
	s_nop 0
	global_load_dwordx4 v[154:157], v[154:155], off
	s_nop 0
	global_load_dwordx4 v[158:161], v[158:159], off offset:3104
	s_nop 0
	global_load_dwordx4 v[162:165], v[162:163], off offset:3104
	s_nop 0
	global_load_dwordx2 v[128:129], v[142:143], off offset:2048
	s_waitcnt lgkmcnt(0)
	s_barrier
	ds_write2_b32 v148, v38, v50 offset1:16
	ds_write2_b32 v148, v39, v51 offset0:64 offset1:80
	ds_write2_b32 v148, v40, v52 offset0:128 offset1:144
	ds_write2_b32 v148, v41, v53 offset0:192 offset1:208
	ds_write2_b32 v148, v54, v22 offset0:32 offset1:48
	ds_write2_b32 v148, v55, v23 offset0:96 offset1:112
	ds_write2_b32 v148, v56, v24 offset0:160 offset1:176
	ds_write2_b32 v148, v57, v25 offset0:224 offset1:240
	ds_write2_b32 v114, v14, v10 offset1:16
	ds_write2_b32 v114, v15, v11 offset0:64 offset1:80
	ds_write2_b32 v114, v16, v12 offset0:128 offset1:144
	ds_write2_b32 v114, v17, v13 offset0:192 offset1:208
	ds_write2_b32 v114, v6, v2 offset0:32 offset1:48
	ds_write2_b32 v114, v7, v3 offset0:96 offset1:112
	ds_write2_b32 v114, v8, v4 offset0:160 offset1:176
	ds_write2_b32 v114, v9, v5 offset0:224 offset1:240
	s_waitcnt lgkmcnt(0)
	s_barrier
	ds_read_b128 v[2:5], v147
	s_waitcnt vmcnt(0)
	v_mfma_f32_16x16x32_bf16 v[22:25], v[158:161], v[154:157], 0
	s_waitcnt lgkmcnt(0)
	v_pk_add_f32 v[6:7], v[4:5], 0 op_sel_hi:[1,0]
	v_pk_add_f32 v[8:9], v[2:3], 0 op_sel_hi:[1,0]
	ds_read_b128 v[2:5], v147 offset:8192
	v_mfma_f32_16x16x32_bf16 v[38:41], v[158:161], v[150:153], 0
	s_waitcnt lgkmcnt(0)
	v_pk_add_f32 v[6:7], v[6:7], v[4:5]
	v_pk_add_f32 v[8:9], v[8:9], v[2:3]
	ds_read_b128 v[2:5], v147 offset:16384
	v_mfma_f32_16x16x32_bf16 v[50:53], v[158:161], v[124:127], 0
	s_waitcnt lgkmcnt(0)
	v_pk_add_f32 v[6:7], v[6:7], v[4:5]
	v_pk_add_f32 v[8:9], v[8:9], v[2:3]
	ds_read_b128 v[2:5], v147 offset:24576
	v_mfma_f32_16x16x32_bf16 v[54:57], v[158:161], v[120:123], 0
	s_waitcnt lgkmcnt(0)
	v_pk_add_f32 v[6:7], v[6:7], v[4:5]
	v_pk_add_f32 v[8:9], v[8:9], v[2:3]
	ds_read_b128 v[2:5], v147 offset:32768
	v_mfma_f32_16x16x32_bf16 v[10:13], v[162:165], v[124:127], 0
	s_waitcnt lgkmcnt(0)
	v_pk_add_f32 v[6:7], v[6:7], v[4:5]
	v_pk_add_f32 v[8:9], v[8:9], v[2:3]
	ds_read_b128 v[2:5], v147 offset:40960
	v_mfma_f32_16x16x32_bf16 v[14:17], v[162:165], v[120:123], 0
	s_waitcnt lgkmcnt(0)
	v_pk_add_f32 v[6:7], v[6:7], v[4:5]
	v_pk_add_f32 v[8:9], v[8:9], v[2:3]
	ds_read_b128 v[2:5], v147 offset:49152
	v_mfma_f32_16x16x32_bf16 v[22:25], v[110:113], v[94:97], v[22:25]
	s_waitcnt lgkmcnt(0)
	v_pk_add_f32 v[6:7], v[6:7], v[4:5]
	v_pk_add_f32 v[8:9], v[8:9], v[2:3]
	ds_read_b128 v[2:5], v147 offset:57344
	v_mfma_f32_16x16x32_bf16 v[38:41], v[110:113], v[90:93], v[38:41]
	s_waitcnt lgkmcnt(0)
	v_pk_add_f32 v[4:5], v[6:7], v[4:5]
	v_lshlrev_b32_e32 v6, 16, v128
	v_mul_f32_e32 v6, 0xbfb8aa3b, v6
	v_exp_f32_e32 v6, v6
	v_pk_add_f32 v[2:3], v[8:9], v[2:3]
	v_mfma_f32_16x16x32_bf16 v[50:53], v[110:113], v[86:89], v[50:53]
	v_mov_b32_e32 v7, v2
	v_add_f32_e32 v6, 1.0, v6
	v_rcp_f32_e32 v109, v6
	v_mov_b32_e32 v6, v100
	v_mfma_f32_16x16x32_bf16 v[54:57], v[110:113], v[82:85], v[54:57]
	v_mul_f32_e64 v6, v108, v6
	v_mul_f32_e64 v7, v109, v7
	v_add_f32_e32 v2, 0, v6
	v_add_f32_e32 v115, v2, v7
	v_and_b32_e32 v2, 0xffff0000, v128
	v_mul_f32_e32 v2, 0xbfb8aa3b, v2
	v_exp_f32_e32 v2, v2
	v_mfma_f32_16x16x32_bf16 v[6:9], v[162:165], v[150:153], 0
	v_add_f32_e32 v2, 1.0, v2
	v_rcp_f32_e32 v107, v2
	v_mov_b32_e32 v2, v101
	v_mfma_f32_16x16x32_bf16 v[6:9], v[116:119], v[90:93], v[6:9]
	v_mul_f32_e64 v2, v106, v2
	v_mul_f32_e64 v3, v107, v3
	v_add_f32_e32 v2, 0, v2
	v_add_f32_e32 v142, v2, v3
	v_lshlrev_b32_e32 v2, 16, v129
	v_mul_f32_e32 v2, 0xbfb8aa3b, v2
	v_exp_f32_e32 v2, v2
	v_mov_b32_e32 v3, v4
	v_mov_b32_e32 v4, v99
	v_add_co_u32_e32 v106, vcc, s4, v140
	v_add_f32_e32 v2, 1.0, v2
	v_rcp_f32_e32 v105, v2
	v_mov_b32_e32 v2, v98
	v_addc_co_u32_e32 v107, vcc, 0, v141, vcc
	v_pk_mul_f32 v[2:3], v[104:105], v[2:3]
	s_mov_b32 s4, 0x610000
	v_add_f32_e32 v2, 0, v2
	v_add_f32_e32 v143, v2, v3
	v_and_b32_e32 v2, 0xffff0000, v129
	v_mul_f32_e32 v2, 0xbfb8aa3b, v2
	v_exp_f32_e32 v2, v2
	v_add_co_u32_e32 v110, vcc, s4, v140
	s_mov_b32 s4, 0x608000
	v_add_f32_e32 v2, 1.0, v2
	v_rcp_f32_e32 v103, v2
	v_addc_co_u32_e32 v111, vcc, 0, v141, vcc
	v_mfma_f32_16x16x32_bf16 v[10:13], v[116:119], v[86:89], v[10:13]
	v_mul_f32_e64 v2, v102, v4
	v_mul_f32_e64 v3, v103, v5
	v_add_f32_e32 v2, 0, v2
	v_add_f32_e32 v149, v2, v3
; __device__ __forceinline__ void sample_branch(const Params& P, int layer, float* red) {
;     const int tid = otid(), w = tid >> 6, lane = tid & 63, fr = lane & 15, fq = lane >> 4;
;     const bf16_t* proj = (const bf16_t*)(P.ws + WS_PROJ); bf16_t* hbuf = (bf16_t*)(P.ws + WS_H);
;     for (int piece = blockIdx.x; piece < 256; piece += gridDim.x) {
;         const int row0 = (piece >> 4) * 32, col0 = (piece & 15) * 64; const size_t r = NPR + row0 + (tid >> 4); const int c = col0 + (tid & 15) * 4;
;         const bf16_t* abase = proj + (size_t)(NPR + row0 + fr) * LDP + w * 128 + fq * 8;
;         const bf16_t* bbase = (const bf16_t*)(P.ws + WS_WBR) + (size_t)layer * 4 * 1048576 + (size_t)(col0 + fr) * 1024 + w * 128 + fq * 8;
;         bf16x8 a[4][2], b[4][4];
;         sg_load4(abase + C_Z, LDP, bbase, 1024, a, b);
;         f32x4 sum = (f32x4){0.f, 0.f, 0.f, 0.f};
;         for (int z = 0; z < 4; ++z) {
;             f32x4 acc[2][4];
; #pragma unroll
;             for (int mt = 0; mt < 2; ++mt)
; #pragma unroll
;                 for (int nt = 0; nt < 4; ++nt) acc[mt][nt] = (f32x4){0.f, 0.f, 0.f, 0.f};
; #pragma unroll
;             for (int ks = 0; ks < 4; ++ks)
; #pragma unroll
;                 for (int mt = 0; mt < 2; ++mt)
; #pragma unroll
;                     for (int nt = 0; nt < 4; ++nt) acc[mt][nt] = __builtin_amdgcn_mfma_f32_16x16x32_bf16(a[ks][mt], b[ks][nt], acc[mt][nt], 0, 0, 0);
;             if (z < 3) { const int ao = z == 0 ? C_BCX : (z == 1 ? C_Q : C_UV); sg_load4(abase + ao, LDP, bbase + (size_t)(z + 1) * 1048576, 1024, a, b); }
;             const u32x2 gv = *(const u32x2*)(proj + r * LDP + C_GATE + z * 1024 + c);
;             __syncthreads();
; #pragma unroll
;             for (int mt = 0; mt < 2; ++mt)
; #pragma unroll
;                 for (int nt = 0; nt < 4; ++nt)
; #pragma unroll
;                     for (int j = 0; j < 4; ++j) red[(w * 32 + mt * 16 + fq * 4 + j) * 64 + nt * 16 + fr] = acc[mt][nt][j];
;             __syncthreads();
;             const f32x4 v = sgemm_reduce(red, tid);
;             sum[0] += sigmoid_fast(bflo(gv[0])) * v[0]; sum[1] += sigmoid_fast(bfhi(gv[0])) * v[1]; sum[2] += sigmoid_fast(bflo(gv[1])) * v[2]; sum[3] += sigmoid_fast(bfhi(gv[1])) * v[3];
;         }
;         u32x2 o; o[0] = pk2(sum[0], sum[1]); o[1] = pk2(sum[2], sum[3]); *(u32x2*)(hbuf + r * 1024 + c) = o;
;         __syncthreads();
;     }
	v_mfma_f32_16x16x32_bf16 v[2:5], v[162:165], v[154:157], 0
	v_mfma_f32_16x16x32_bf16 v[2:5], v[116:119], v[94:97], v[2:5]
	v_mfma_f32_16x16x32_bf16 v[14:17], v[116:119], v[82:85], v[14:17]
	v_add_co_u32_e32 v116, vcc, s4, v140
	s_mov_b32 s4, 0x600000
	s_nop 0
	v_addc_co_u32_e32 v117, vcc, 0, v141, vcc
	v_add_co_u32_e32 v120, vcc, s4, v140
	s_mov_b32 s4, 0x6d000
	s_nop 0
	v_addc_co_u32_e32 v121, vcc, 0, v141, vcc
	v_mfma_f32_16x16x32_bf16 v[2:5], v[78:81], v[70:73], v[2:5]
	v_add_co_u32_e32 v124, vcc, s4, v138
	s_movk_i32 s4, 0x5000
	v_mfma_f32_16x16x32_bf16 v[6:9], v[78:81], v[66:69], v[6:9]
	v_addc_co_u32_e32 v125, vcc, 0, v139, vcc
	v_add_co_u32_e32 v128, vcc, s17, v138
	v_mfma_f32_16x16x32_bf16 v[10:13], v[78:81], v[62:65], v[10:13]
	s_nop 0
	v_addc_co_u32_e32 v129, vcc, 0, v139, vcc
	v_mfma_f32_16x16x32_bf16 v[14:17], v[78:81], v[58:61], v[14:17]
	v_mfma_f32_16x16x32_bf16 v[22:25], v[74:77], v[70:73], v[22:25]
	v_mfma_f32_16x16x32_bf16 v[38:41], v[74:77], v[66:69], v[38:41]
	v_mfma_f32_16x16x32_bf16 v[50:53], v[74:77], v[62:65], v[50:53]
	v_mfma_f32_16x16x32_bf16 v[54:57], v[74:77], v[58:61], v[54:57]
	v_mfma_f32_16x16x32_bf16 v[2:5], v[46:49], v[34:37], v[2:5]
	v_mfma_f32_16x16x32_bf16 v[6:9], v[46:49], v[30:33], v[6:9]
	v_mfma_f32_16x16x32_bf16 v[10:13], v[46:49], v[26:29], v[10:13]
	v_mfma_f32_16x16x32_bf16 v[14:17], v[46:49], v[18:21], v[14:17]
	global_load_dwordx4 v[46:49], v[120:121], off offset:192
	v_mfma_f32_16x16x32_bf16 v[22:25], v[42:45], v[34:37], v[22:25]
	global_load_dwordx4 v[34:37], v[106:107], off offset:192
	v_mfma_f32_16x16x32_bf16 v[30:33], v[42:45], v[30:33], v[38:41]
	v_mfma_f32_16x16x32_bf16 v[26:29], v[42:45], v[26:29], v[50:53]
	s_nop 1
	global_load_dwordx4 v[38:41], v[110:111], off offset:192
	v_mfma_f32_16x16x32_bf16 v[18:21], v[42:45], v[18:21], v[54:57]
	global_load_dwordx4 v[42:45], v[116:117], off offset:192
	global_load_dwordx4 v[50:53], v[124:125], off offset:2272
	s_nop 0
	global_load_dwordx4 v[54:57], v[128:129], off offset:2272
	global_load_dwordx4 v[58:61], v[106:107], off offset:128
	global_load_dwordx4 v[62:65], v[110:111], off offset:128
	global_load_dwordx4 v[66:69], v[116:117], off offset:128
	global_load_dwordx4 v[70:73], v[120:121], off offset:128
	global_load_dwordx4 v[74:77], v[124:125], off offset:2208
	global_load_dwordx4 v[78:81], v[128:129], off offset:2208
	global_load_dwordx4 v[82:85], v[106:107], off offset:64
	global_load_dwordx4 v[86:89], v[110:111], off offset:64
	global_load_dwordx4 v[90:93], v[116:117], off offset:64
	global_load_dwordx4 v[94:97], v[120:121], off offset:64
	global_load_dwordx4 v[98:101], v[124:125], off offset:2144
	global_load_dwordx4 v[102:105], v[128:129], off offset:2144
	s_nop 0
	global_load_dwordx4 v[106:109], v[106:107], off
	s_nop 0
	global_load_dwordx4 v[110:113], v[110:111], off
	s_nop 0
	global_load_dwordx4 v[116:119], v[116:117], off
	s_nop 0
	global_load_dwordx4 v[120:123], v[120:121], off
	s_nop 0
	global_load_dwordx4 v[124:127], v[124:125], off offset:2080
	s_nop 0
	global_load_dwordx4 v[138:141], v[128:129], off offset:2080
	v_add_co_u32_e32 v128, vcc, s4, v136
	s_nop 1
	v_addc_co_u32_e32 v129, vcc, 0, v137, vcc
	global_load_dwordx2 v[128:129], v[128:129], off offset:2080
	s_waitcnt lgkmcnt(0)
	s_barrier
	ds_write2_b32 v148, v2, v6 offset1:16
	ds_write2_b32 v148, v3, v7 offset0:64 offset1:80
	ds_write2_b32 v148, v4, v8 offset0:128 offset1:144
	ds_write2_b32 v148, v5, v9 offset0:192 offset1:208
	ds_write2_b32 v148, v10, v14 offset0:32 offset1:48
	ds_write2_b32 v148, v11, v15 offset0:96 offset1:112
	ds_write2_b32 v148, v12, v16 offset0:160 offset1:176
	ds_write2_b32 v148, v13, v17 offset0:224 offset1:240
	ds_write2_b32 v114, v22, v30 offset1:16
	ds_write2_b32 v114, v23, v31 offset0:64 offset1:80
	ds_write2_b32 v114, v24, v32 offset0:128 offset1:144
	ds_write2_b32 v114, v25, v33 offset0:192 offset1:208
	ds_write2_b32 v114, v26, v18 offset0:32 offset1:48
	ds_write2_b32 v114, v27, v19 offset0:96 offset1:112
	ds_write2_b32 v114, v28, v20 offset0:160 offset1:176
	ds_write2_b32 v114, v29, v21 offset0:224 offset1:240
	s_waitcnt vmcnt(0)
	v_mfma_f32_16x16x32_bf16 v[2:5], v[138:141], v[120:123], 0
	s_waitcnt lgkmcnt(0)
	s_barrier
	v_mfma_f32_16x16x32_bf16 v[14:17], v[138:141], v[106:109], 0
	v_mfma_f32_16x16x32_bf16 v[18:21], v[124:127], v[120:123], 0
	v_mfma_f32_16x16x32_bf16 v[30:33], v[124:127], v[106:109], 0
	v_mfma_f32_16x16x32_bf16 v[2:5], v[102:105], v[94:97], v[2:5]
	v_mfma_f32_16x16x32_bf16 v[14:17], v[102:105], v[82:85], v[14:17]
	v_mfma_f32_16x16x32_bf16 v[18:21], v[98:101], v[94:97], v[18:21]
	v_mfma_f32_16x16x32_bf16 v[30:33], v[98:101], v[82:85], v[30:33]
	v_mfma_f32_16x16x32_bf16 v[10:13], v[138:141], v[110:113], 0
	v_mfma_f32_16x16x32_bf16 v[26:29], v[124:127], v[110:113], 0
	v_mfma_f32_16x16x32_bf16 v[2:5], v[78:81], v[70:73], v[2:5]
	v_mfma_f32_16x16x32_bf16 v[14:17], v[78:81], v[58:61], v[14:17]
	v_mfma_f32_16x16x32_bf16 v[18:21], v[74:77], v[70:73], v[18:21]
	v_mfma_f32_16x16x32_bf16 v[30:33], v[74:77], v[58:61], v[30:33]
	v_mfma_f32_16x16x32_bf16 v[10:13], v[102:105], v[86:89], v[10:13]
	v_mfma_f32_16x16x32_bf16 v[26:29], v[98:101], v[86:89], v[26:29]
	v_mfma_f32_16x16x32_bf16 v[6:9], v[138:141], v[116:119], 0
	v_mfma_f32_16x16x32_bf16 v[22:25], v[124:127], v[116:119], 0
	v_mfma_f32_16x16x32_bf16 v[2:5], v[54:57], v[46:49], v[2:5]
	v_mfma_f32_16x16x32_bf16 v[14:17], v[54:57], v[34:37], v[14:17]
	v_mfma_f32_16x16x32_bf16 v[18:21], v[50:53], v[46:49], v[18:21]
	v_add_co_u32_e32 v46, vcc, s74, v136
	v_mfma_f32_16x16x32_bf16 v[30:33], v[50:53], v[34:37], v[30:33]
	v_and_b32_e32 v34, 0xffff0000, v129
	v_mul_f32_e32 v34, 0xbfb8aa3b, v34
	v_addc_co_u32_e32 v47, vcc, 0, v137, vcc
	v_exp_f32_e32 v34, v34
	global_load_dwordx2 v[46:47], v[46:47], off offset:32
	v_mfma_f32_16x16x32_bf16 v[10:13], v[78:81], v[62:65], v[10:13]
	v_add_f32_e32 v34, 1.0, v34
	v_mfma_f32_16x16x32_bf16 v[26:29], v[74:77], v[62:65], v[26:29]
	v_mfma_f32_16x16x32_bf16 v[6:9], v[102:105], v[90:93], v[6:9]
	v_mfma_f32_16x16x32_bf16 v[22:25], v[98:101], v[90:93], v[22:25]
	v_mfma_f32_16x16x32_bf16 v[10:13], v[54:57], v[38:41], v[10:13]
	v_mfma_f32_16x16x32_bf16 v[26:29], v[50:53], v[38:41], v[26:29]
	v_rcp_f32_e32 v38, v34
	ds_read_b128 v[34:37], v147
	v_lshlrev_b32_e32 v39, 16, v129
	v_mfma_f32_16x16x32_bf16 v[6:9], v[78:81], v[66:69], v[6:9]
	v_mul_f32_e32 v39, 0xbfb8aa3b, v39
	v_exp_f32_e32 v39, v39
	s_waitcnt lgkmcnt(0)
; __device__ __forceinline__ float bflo(unsigned v) { return __uint_as_float(v << 16); }
; __device__ __forceinline__ float bfhi(unsigned v) { return __uint_as_float(v & 0xffff0000u); }
; __device__ __forceinline__ unsigned pk2(float lo, float hi) { unsigned r; asm("v_cvt_pk_bf16_f32 %0, %1, %2" : "=v"(r) : "v"(lo), "v"(hi)); return r; }
; __device__ __forceinline__ float sigmoid_fast(float x) { return __builtin_amdgcn_rcpf(1.f + __expf(-x)); }
; __device__ __forceinline__ f32x4 sgemm_reduce(const float* red, int tid) {
;     const int row = tid >> 4, c4 = (tid & 15) * 4; f32x4 sacc = (f32x4){0.f, 0.f, 0.f, 0.f};
; #pragma unroll
;     for (int w = 0; w < 8; ++w) sacc += *(const f32x4*)(red + (w * 32 + row) * 64 + c4);
;     return sacc;
; }
; __device__ __forceinline__ void sample_branch(const Params& P, int layer, float* red) {
;     ...
;             const u32x2 gv = *(const u32x2*)(proj + r * LDP + C_GATE + z * 1024 + c);
;             __syncthreads();
; #pragma unroll
;             for (int mt = 0; mt < 2; ++mt)
; #pragma unroll
;                 for (int nt = 0; nt < 4; ++nt)
; #pragma unroll
;                     for (int j = 0; j < 4; ++j) red[(w * 32 + mt * 16 + fq * 4 + j) * 64 + nt * 16 + fr] = acc[mt][nt][j];
;             __syncthreads();
;             const f32x4 v = sgemm_reduce(red, tid);
;             sum[0] += sigmoid_fast(bflo(gv[0])) * v[0]; sum[1] += sigmoid_fast(bfhi(gv[0])) * v[1]; sum[2] += sigmoid_fast(bflo(gv[1])) * v[2]; sum[3] += sigmoid_fast(bfhi(gv[1])) * v[3];
;         }
;         u32x2 o; o[0] = pk2(sum[0], sum[1]); o[1] = pk2(sum[2], sum[3]); *(u32x2*)(hbuf + r * 1024 + c) = o;
;         __syncthreads();
;     }
	v_pk_add_f32 v[40:41], v[36:37], 0 op_sel_hi:[1,0]
	v_mfma_f32_16x16x32_bf16 v[22:25], v[74:77], v[66:69], v[22:25]
	v_add_f32_e32 v39, 1.0, v39
	v_mfma_f32_16x16x32_bf16 v[6:9], v[54:57], v[42:45], v[6:9]
	v_mfma_f32_16x16x32_bf16 v[22:25], v[50:53], v[42:45], v[22:25]
	v_add_f32_e64 v42, v34, 0
	v_add_f32_e64 v43, v35, 0
	ds_read_b128 v[34:37], v147 offset:8192
	s_waitcnt lgkmcnt(0)
	v_pk_add_f32 v[40:41], v[40:41], v[36:37]
	v_pk_add_f32 v[42:43], v[42:43], v[34:35]
	ds_read_b128 v[34:37], v147 offset:16384
	s_waitcnt lgkmcnt(0)
	v_pk_add_f32 v[40:41], v[40:41], v[36:37]
	v_pk_add_f32 v[42:43], v[42:43], v[34:35]
	ds_read_b128 v[34:37], v147 offset:24576
	s_waitcnt lgkmcnt(0)
	v_pk_add_f32 v[40:41], v[40:41], v[36:37]
	v_pk_add_f32 v[42:43], v[42:43], v[34:35]
	ds_read_b128 v[34:37], v147 offset:32768
	s_waitcnt lgkmcnt(0)
	v_pk_add_f32 v[40:41], v[40:41], v[36:37]
	v_pk_add_f32 v[42:43], v[42:43], v[34:35]
	ds_read_b128 v[34:37], v147 offset:40960
	s_waitcnt lgkmcnt(0)
	v_pk_add_f32 v[40:41], v[40:41], v[36:37]
	v_pk_add_f32 v[42:43], v[42:43], v[34:35]
	ds_read_b128 v[34:37], v147 offset:49152
	s_waitcnt lgkmcnt(0)
	v_pk_add_f32 v[40:41], v[40:41], v[36:37]
	v_pk_add_f32 v[42:43], v[42:43], v[34:35]
	ds_read_b128 v[34:37], v147 offset:57344
	s_waitcnt lgkmcnt(0)
	s_barrier
	ds_write2_b32 v148, v2, v6 offset1:16
	ds_write2_b32 v148, v3, v7 offset0:64 offset1:80
	ds_write2_b32 v148, v4, v8 offset0:128 offset1:144
	ds_write2_b32 v148, v5, v9 offset0:192 offset1:208
	ds_write2_b32 v148, v10, v14 offset0:32 offset1:48
	ds_write2_b32 v148, v11, v15 offset0:96 offset1:112
	ds_write2_b32 v148, v12, v16 offset0:160 offset1:176
	ds_write2_b32 v148, v13, v17 offset0:224 offset1:240
	ds_write2_b32 v114, v18, v22 offset1:16
	ds_write2_b32 v114, v19, v23 offset0:64 offset1:80
	ds_write2_b32 v114, v20, v24 offset0:128 offset1:144
	ds_write2_b32 v114, v21, v25 offset0:192 offset1:208
	ds_write2_b32 v114, v26, v30 offset0:32 offset1:48
	ds_write2_b32 v114, v27, v31 offset0:96 offset1:112
	ds_write2_b32 v114, v28, v32 offset0:160 offset1:176
	ds_write2_b32 v114, v29, v33 offset0:224 offset1:240
	s_waitcnt lgkmcnt(0)
	s_barrier
	ds_read_b128 v[2:5], v147
	v_pk_add_f32 v[36:37], v[40:41], v[36:37]
	v_rcp_f32_e32 v40, v39
	v_and_b32_e32 v39, 0xffff0000, v128
	v_mul_f32_e32 v39, 0xbfb8aa3b, v39
	s_waitcnt lgkmcnt(0)
	v_pk_add_f32 v[6:7], v[4:5], 0 op_sel_hi:[1,0]
	v_pk_add_f32 v[8:9], v[2:3], 0 op_sel_hi:[1,0]
	ds_read_b128 v[2:5], v147 offset:8192
	v_exp_f32_e32 v39, v39
	v_pk_add_f32 v[34:35], v[42:43], v[34:35]
	s_waitcnt lgkmcnt(0)
	v_pk_add_f32 v[6:7], v[6:7], v[4:5]
	v_pk_add_f32 v[8:9], v[8:9], v[2:3]
	ds_read_b128 v[2:5], v147 offset:16384
	v_add_f32_e32 v39, 1.0, v39
	v_rcp_f32_e32 v42, v39
	v_lshlrev_b32_e32 v39, 16, v128
	v_mul_f32_e32 v39, 0xbfb8aa3b, v39
	s_waitcnt lgkmcnt(0)
	v_pk_add_f32 v[6:7], v[6:7], v[4:5]
	v_pk_add_f32 v[8:9], v[8:9], v[2:3]
	ds_read_b128 v[2:5], v147 offset:24576
	v_exp_f32_e32 v39, v39
	s_waitcnt lgkmcnt(0)
	v_pk_add_f32 v[6:7], v[6:7], v[4:5]
	v_pk_add_f32 v[8:9], v[8:9], v[2:3]
	ds_read_b128 v[2:5], v147 offset:32768
	v_add_f32_e32 v39, 1.0, v39
	v_rcp_f32_e32 v44, v39
	s_waitcnt lgkmcnt(0)
	v_pk_add_f32 v[6:7], v[6:7], v[4:5]
	v_pk_add_f32 v[8:9], v[8:9], v[2:3]
	ds_read_b128 v[2:5], v147 offset:40960
	s_waitcnt lgkmcnt(0)
	v_pk_add_f32 v[6:7], v[6:7], v[4:5]
	v_pk_add_f32 v[8:9], v[8:9], v[2:3]
	ds_read_b128 v[2:5], v147 offset:49152
	s_waitcnt lgkmcnt(0)
	v_pk_add_f32 v[6:7], v[6:7], v[4:5]
	v_pk_add_f32 v[8:9], v[8:9], v[2:3]
	ds_read_b128 v[2:5], v147 offset:57344
	s_waitcnt lgkmcnt(0)
	v_pk_add_f32 v[4:5], v[6:7], v[4:5]
	s_waitcnt vmcnt(0)
	v_lshlrev_b32_e32 v6, 16, v46
	v_mul_f32_e32 v6, 0xbfb8aa3b, v6
	v_exp_f32_e32 v6, v6
	v_pk_add_f32 v[2:3], v[8:9], v[2:3]
	v_add_f32_e32 v6, 1.0, v6
	v_rcp_f32_e32 v45, v6
	v_mov_b32_e32 v6, v34
	v_mov_b32_e32 v7, v2
	v_pk_mul_f32 v[6:7], v[44:45], v[6:7]
	s_nop 0
	v_add_f32_e32 v2, v115, v6
	v_add_f32_e32 v6, v2, v7
	v_and_b32_e32 v2, 0xffff0000, v46
	v_mul_f32_e32 v2, 0xbfb8aa3b, v2
	v_exp_f32_e32 v2, v2
	s_nop 0
	v_add_f32_e32 v2, 1.0, v2
	v_rcp_f32_e32 v43, v2
	v_mov_b32_e32 v2, v35
	v_pk_mul_f32 v[2:3], v[42:43], v[2:3]
	s_nop 0
	v_add_f32_e32 v2, v142, v2
	v_add_f32_e32 v7, v2, v3
	v_lshlrev_b32_e32 v2, 16, v47
	v_mul_f32_e32 v2, 0xbfb8aa3b, v2
	v_exp_f32_e32 v2, v2
	v_mov_b32_e32 v3, v4
	v_mov_b32_e32 v4, v37
	v_add_f32_e32 v2, 1.0, v2
	v_rcp_f32_e32 v41, v2
	v_mov_b32_e32 v2, v36
	v_pk_mul_f32 v[2:3], v[40:41], v[2:3]
	s_nop 0
	v_add_f32_e32 v2, v143, v2
	v_add_f32_e32 v8, v2, v3
	v_and_b32_e32 v2, 0xffff0000, v47
	v_mul_f32_e32 v2, 0xbfb8aa3b, v2
	v_exp_f32_e32 v2, v2
	s_nop 0
	v_add_f32_e32 v2, 1.0, v2
	v_rcp_f32_e32 v39, v2
	s_nop 0
	v_pk_mul_f32 v[2:3], v[38:39], v[4:5]
	v_lshlrev_b64 v[4:5], 11, v[134:135]
	v_add_f32_e32 v2, v149, v2
	v_lshl_add_u64 v[4:5], s[82:83], 0, v[4:5]
	v_add_f32_e32 v3, v2, v3
	v_lshl_add_u64 v[4:5], v[4:5], 0, v[0:1]
	v_cvt_pk_bf16_f32 v2, v6, v7
	v_cvt_pk_bf16_f32 v3, v8, v3
	global_store_dwordx2 v[4:5], v[2:3], off
	s_waitcnt lgkmcnt(0)
	s_barrier
	s_cbranch_scc0 .LBB0_161

; __device__ __forceinline__ void grid_bar(unsigned* ctr, unsigned& epoch) {
;     ...
;         const unsigned target = epoch * gridDim.x;
;         while (__hip_atomic_load(ctr, __ATOMIC_RELAXED, __HIP_MEMORY_SCOPE_AGENT) < target) __builtin_amdgcn_s_sleep(1);
;         __builtin_amdgcn_fence(__ATOMIC_ACQUIRE, "agent");
.LBB0_1020:
	v_mov_b64_e32 v[2:3], s[4:5]
	flat_load_dword v0, v[2:3] sc1
	s_waitcnt vmcnt(0) lgkmcnt(0)
	v_readfirstlane_b32 s11, v0
	s_cmp_ge_u32 s11, s10
	s_cselect_b64 s[12:13], -1, 0
	s_and_b64 s[12:13], exec, s[12:13]
	s_or_b64 s[8:9], s[12:13], s[8:9]
	s_andn2_b64 exec, exec, s[8:9]
	s_cbranch_execnz .LBB0_1020
